# speedup vs baseline: 1.0016x; 1.0016x over previous
; DEVI int otid() { int t = threadIdx.x; asm volatile("" : "+v"(t)); return t; }
; DEVI int v_st(int k, int c) { const int kk = (k & ~0xC) | ((k & 4) << 1) | ((k & 8) >> 1); return ((kk >> 3) * 4 + (c >> 5)) * 512 + ((kk & 7) * 32 + (c & 31)) * 2; }
; DEVI int v_rd_base(int lane) { return ((lane & 3) << 3) | (((lane >> 2) & 3) << 6) | (((lane >> 4) & 1) << 5) | (((lane >> 5) & 1) << 8); }
; template <bool FIX>
; DEVI void attn_item(const bfr* __restrict__ Qb, const bfr* __restrict__ Kh, const bfr* __restrict__ Vh, bfr* __restrict__ Ob, int seq, char* lds, float negBC) {
;   const int tid = otid(), wid = tid >> 6, lane = tid & 63, r32 = lane & 31, hi = lane >> 5;
;   char* V_lds = lds; char* K_lds = lds + 2 * SHM_V;
;   float* ws = (float*)(lds + 2 * SHM_V + 2 * SHM_K) + wid * 64; float* li_l = ws; float* al_l = ws + 32;
;   float m_reg = -1e30f, l_reg = 0; f32x16 o[4] = {}; bf16x8 qr[12];
;   const bfr* Qw = Qb + (long)(wid * QBLK + r32) * LDQ + hi * 8;
; #pragma unroll
;   for (int d0 = 0; d0 < 12; ++d0) qr[d0] = *reinterpret_cast<const bf16x8*>(Qw + d0 * 16);
;   const int sr = tid >> 4, sc = (tid & 15) * 8, vst0 = v_st(sr, sc), vst1 = v_st(32 + sr, sc);
;   const int kr = tid >> 3, kc = 128 + (tid & 7) * 8;
;   const int vb0 = (int)(uintptr_t)V_lds + v_rd_base(lane);
;   struct { bf16x8 vs0, vs1, ks0, ks1, ks2; } sr_[1];
;     ...
;   f32x16 pA0, pA1; float mnA, alA; bf16x8 pa0, pa1, pa2, pa3; const int NT = seq / KVBLK;
;   SLOAD(0, 0); asm volatile("s_waitcnt vmcnt(0)" ::: "memory"); SWRITE(0, 0); SLOAD(0, KVBLK); __syncthreads();
.LBB0_118:
	s_and_b64 vcc, exec, s[0:1]
	s_cbranch_vccz .LBB0_95
	v_mov_b32_e32 v184, v164
	s_movk_i32 s0, 0xffe0
	v_ashrrev_i32_e32 v0, 1, v184
	v_bfe_u32 v183, v184, 5, 1
	v_and_b32_e32 v170, 0xffffffe0, v0
	v_bfi_b32 v2, s0, v0, v184
	v_mov_b64_e32 v[0:1], s[8:9]
	s_movk_i32 s2, 0x1800
	v_mad_i64_i32 v[0:1], s[0:1], v2, s2, v[0:1]
	v_lshlrev_b32_e32 v166, 4, v183
	v_lshl_add_u64 v[0:1], v[0:1], 0, v[166:167]
	global_load_dwordx4 v[140:143], v[0:1], off
	global_load_dwordx4 v[136:139], v[0:1], off offset:32
	global_load_dwordx4 v[132:135], v[0:1], off offset:64
	global_load_dwordx4 v[128:131], v[0:1], off offset:96
	global_load_dwordx4 v[124:127], v[0:1], off offset:128
	global_load_dwordx4 v[120:123], v[0:1], off offset:160
	global_load_dwordx4 v[116:119], v[0:1], off offset:192
	global_load_dwordx4 v[112:115], v[0:1], off offset:224
	global_load_dwordx4 v[108:111], v[0:1], off offset:256
	global_load_dwordx4 v[104:107], v[0:1], off offset:288
	global_load_dwordx4 v[100:103], v[0:1], off offset:320
	global_load_dwordx4 v[96:99], v[0:1], off offset:352
	v_ashrrev_i32_e32 v0, 4, v184
	v_and_b32_e32 v2, 0xfffff0, v0
	v_lshlrev_b32_e32 v3, 1, v0
	v_lshlrev_b32_e32 v28, 3, v184
	v_and_or_b32 v2, v3, 8, v2
	v_lshrrev_b32_e32 v2, 1, v2
	v_bfe_u32 v4, v28, 5, 2
	v_or_b32_e32 v2, v2, v4
	v_lshrrev_b32_e32 v3, 1, v0
	v_lshlrev_b32_e32 v5, 9, v2
	v_and_b32_e32 v2, 3, v0
	v_and_b32_e32 v1, 0x78, v28
	v_and_or_b32 v2, v3, 4, v2
	v_lshlrev_b32_e32 v3, 6, v2
	v_lshlrev_b32_e32 v2, 1, v1
	v_and_b32_e32 v1, 48, v2
	v_add_u32_e32 v20, 32, v0
	v_or3_b32 v185, v5, v3, v1
	v_and_b32_e32 v5, 0xfffff0, v20
	v_lshlrev_b32_e32 v6, 1, v20
	v_and_or_b32 v5, v6, 8, v5
	v_lshrrev_b32_e32 v5, 1, v5
	v_or_b32_e32 v4, v5, v4
	v_lshlrev_b32_e32 v4, 9, v4
	v_or3_b32 v186, v4, v3, v1
	v_lshrrev_b32_e32 v191, 7, v184
	v_lshlrev_b32_e32 v185, 11, v191
	v_bfe_u32 v191, v184, 2, 2
	v_lshl_or_b32 v185, v191, 9, v185
	v_bfe_u32 v191, v184, 4, 3
	v_lshl_or_b32 v185, v191, 6, v185
	v_and_b32_e32 v191, 3, v184
	v_lshl_or_b32 v185, v191, 4, v185
	v_add_u32_e32 v186, 0x2000, v185
	v_ashrrev_i32_e32 v1, 31, v0
	v_lshlrev_b64 v[6:7], 12, v[0:1]
	v_lshl_add_u64 v[6:7], s[82:83], 0, v[6:7]
	v_mov_b32_e32 v3, v167
	v_lshl_add_u64 v[6:7], v[6:7], 0, v[2:3]
	v_ashrrev_i32_e32 v21, 31, v20
	global_load_dwordx4 v[8:11], v[6:7], off
	v_lshlrev_b64 v[6:7], 12, v[20:21]
	v_lshl_add_u64 v[6:7], s[82:83], 0, v[6:7]
	v_lshl_add_u64 v[6:7], v[6:7], 0, v[2:3]
	v_ashrrev_i32_e32 v29, 3, v184
	v_lshlrev_b32_e32 v30, 4, v184
	global_load_dwordx4 v[12:15], v[6:7], off
	v_mov_b64_e32 v[6:7], s[34:35]
	v_and_b32_e32 v4, 0x70, v30
	v_mad_i64_i32 v[16:17], s[0:1], v0, s2, v[6:7]
	v_mad_i64_i32 v[24:25], s[0:1], v29, s2, v[6:7]
	v_mov_b32_e32 v5, v167
	v_lshl_add_u64 v[16:17], v[16:17], 0, v[2:3]
	v_mad_i64_i32 v[20:21], s[0:1], v20, s2, v[6:7]
	v_lshl_add_u64 v[24:25], v[24:25], 0, v[4:5]
	global_load_dwordx4 v[16:19], v[16:17], off
	v_lshl_add_u64 v[20:21], v[20:21], 0, v[2:3]
	global_load_dwordx4 v[24:27], v[24:25], off offset:256
	s_movk_i32 s4, 0x190
	global_load_dwordx4 v[20:23], v[20:21], off
	s_waitcnt vmcnt(0)
	v_mad_u64_u32 v[172:173], s[0:1], v0, s4, v[2:3]
	v_add_u32_e32 v1, 64, v29
	v_and_b32_e32 v182, 31, v184
	v_mov_b32_e32 v173, 0
	v_and_b32_e32 v171, 63, v184
	v_lshl_add_u32 v174, v0, 12, v2
	v_add_u32_e32 v175, 0x20000, v174
	v_mad_u32_u24 v176, v0, s2, v2
	v_add_u32_e32 v177, 0x30000, v176
	v_mad_u32_u24 v178, v29, s2, v4
	v_mul_u32_u24_e32 v189, 0x190, v182
	v_mov_b32_e32 v31, v173
	v_mov_b32_e32 v32, 0
	v_mov_b32_e32 v33, v173
	v_mov_b32_e32 v34, v173
	v_mov_b32_e32 v35, v173
	v_mov_b32_e32 v36, v173
	v_mov_b32_e32 v37, v173
	v_mov_b32_e32 v38, v173
	v_mov_b32_e32 v39, v173
	v_mov_b32_e32 v40, v173
	v_mov_b32_e32 v41, v173
	v_mov_b32_e32 v42, v173
	v_mov_b32_e32 v43, v173
	v_mov_b32_e32 v44, v173
	v_mov_b32_e32 v45, v173
	v_mov_b32_e32 v46, v173
	v_mov_b32_e32 v47, v173
	v_mov_b32_e32 v48, 0
	v_mov_b32_e32 v49, v173
	v_mov_b32_e32 v50, v173
	v_mov_b32_e32 v51, v173
	v_mov_b32_e32 v52, v173
	v_mov_b32_e32 v53, v173
	v_mov_b32_e32 v54, v173
	s_waitcnt vmcnt(0) lgkmcnt(0)
	ds_write_b128 v185, v[8:11]
	ds_write_b128 v186, v[12:15]
	v_mad_u64_u32 v[8:9], s[0:1], v29, s4, v[4:5]
	ds_write_b128 v172, v[16:19] offset:32768
	ds_write_b128 v172, v[20:23] offset:45568
	v_add_u32_e32 v188, 0x100, v8
	ds_write_b128 v8, v[24:27] offset:33024
	v_add_u32_e32 v8, 64, v0
	v_ashrrev_i32_e32 v9, 31, v8
	v_lshlrev_b64 v[10:11], 12, v[8:9]
	v_lshl_add_u64 v[10:11], s[82:83], 0, v[10:11]
	v_mad_i64_i32 v[8:9], s[0:1], v8, s2, v[6:7]
	v_lshl_add_u64 v[10:11], v[10:11], 0, v[2:3]
	v_lshl_add_u64 v[8:9], v[8:9], 0, v[2:3]
	global_load_dwordx4 v[144:147], v[10:11], off
	global_load_dwordx4 v[152:155], v[8:9], off
	v_add_u32_e32 v10, 0x60, v0
	v_ashrrev_i32_e32 v11, 31, v10
	v_lshlrev_b64 v[12:13], 12, v[10:11]
	v_lshl_add_u64 v[12:13], s[82:83], 0, v[12:13]
	v_mad_i64_i32 v[8:9], s[0:1], v10, s2, v[6:7]
	v_mad_i64_i32 v[6:7], s[0:1], v1, s2, v[6:7]
	v_lshl_add_u64 v[12:13], v[12:13], 0, v[2:3]
	v_lshl_add_u64 v[8:9], v[8:9], 0, v[2:3]
	v_lshl_add_u64 v[6:7], v[6:7], 0, v[4:5]
	global_load_dwordx4 v[148:151], v[12:13], off
	global_load_dwordx4 v[156:159], v[8:9], off
	global_load_dwordx4 v[160:163], v[6:7], off offset:256
	v_lshlrev_b32_e32 v1, 1, v184
	v_and_b32_e32 v1, 32, v1
	s_movk_i32 s0, 0x118
	v_and_or_b32 v1, v28, s0, v1
	v_and_or_b32 v187, v30, s77, v1
	s_add_i32 s0, s64, -1
	s_mov_b32 s1, 0
	v_mov_b32_e32 v0, 0
	v_mov_b32_e32 v1, v173
	v_mov_b32_e32 v2, v173
	v_mov_b32_e32 v3, v173
	v_mov_b32_e32 v4, v173
	v_mov_b32_e32 v5, v173
	v_mov_b32_e32 v6, v173
	v_mov_b32_e32 v7, v173
	v_mov_b32_e32 v8, v173
	v_mov_b32_e32 v9, v173
	v_mov_b32_e32 v10, v173
	v_mov_b32_e32 v11, v173
	v_mov_b32_e32 v12, v173
	v_mov_b32_e32 v13, v173
	v_mov_b32_e32 v14, v173
	v_mov_b32_e32 v15, v173
	v_mov_b32_e32 v16, 0
	v_mov_b32_e32 v17, v173
	v_mov_b32_e32 v18, v173
	v_mov_b32_e32 v19, v173
	v_mov_b32_e32 v20, v173
	v_mov_b32_e32 v21, v173
	v_mov_b32_e32 v22, v173
	v_mov_b32_e32 v23, v173
	v_mov_b32_e32 v24, v173
	v_mov_b32_e32 v25, v173
	v_mov_b32_e32 v26, v173
	v_mov_b32_e32 v27, v173
	v_mov_b32_e32 v28, v173
	v_mov_b32_e32 v29, v173
	v_mov_b32_e32 v30, v173
	v_mov_b32_e32 v55, v173
	v_mov_b32_e32 v56, v173
	v_mov_b32_e32 v57, v173
	v_mov_b32_e32 v58, v173
	v_mov_b32_e32 v59, v173
	v_mov_b32_e32 v60, v173
	v_mov_b32_e32 v61, v173
	v_mov_b32_e32 v62, v173
	v_mov_b32_e32 v63, v173
	s_waitcnt lgkmcnt(0)
	s_barrier
	s_add_u32 s34, s34, 0xc0000
	s_addc_u32 s35, s35, 0
	s_add_u32 s82, s82, 0x80000
	s_addc_u32 s83, s83, 0
	s_mov_b32 s100, 0x4000
	s_add_i32 s6, s64, -2
	s_branch .LBB0_121
; #define SCHEDB() __builtin_amdgcn_sched_barrier(0)
; template <bool FIX>
; DEVI void attn_item(const bfr* __restrict__ Qb, const bfr* __restrict__ Kh, const bfr* __restrict__ Vh, bfr* __restrict__ Ob, int seq, char* lds, float negBC) {
;     ...
;   for (int j = 0; j < NT; ++j) {
;     const int buf = j & 1;
;     SCHEDB(); qkt(pA0, pA1, K_lds + buf * SHM_K, qr, r32, hi);
;     if (j + 1 < NT) { SWRITE(buf ^ 1, 0); if (j + 2 < NT) SLOAD(0, (j + 2) * KVBLK); }
.LBB0_121:
	s_and_b32 s2, s1, 1
	s_mul_i32 s4, s2, 0x6400
	v_add3_u32 v191, s4, v189, v166
	s_xor_b32 s4, s4, 0x6400
	s_cmp_eq_u32 s100, 0x4000
	s_cselect_b32 s101, 0x15000, 0
	s_cmp_eq_u32 s100, 0
	s_cselect_b32 s101, 0x4000, s101
	v_add_u32_e32 v194, s101, v187
	ds_read_b128 v[196:199], v191 offset:32768
	ds_read_b128 v[200:203], v191 offset:32800
	ds_read_b128 v[204:207], v191 offset:32832
	ds_read_b128 v[224:227], v191 offset:32864
	ds_read_b128 v[228:231], v191 offset:32896
	ds_read_b128 v[232:235], v191 offset:32928
	ds_read_b128 v[236:239], v191 offset:32960
	ds_read_b128 v[240:243], v191 offset:32992
	v_cvt_pk_bf16_f32 v208, v80, v81
	v_cvt_pk_bf16_f32 v209, v82, v83
	v_cvt_pk_bf16_f32 v210, v84, v85
	v_cvt_pk_bf16_f32 v211, v86, v87
	v_cvt_pk_bf16_f32 v212, v88, v89
	v_cvt_pk_bf16_f32 v213, v90, v91
	v_cvt_pk_bf16_f32 v214, v92, v93
	v_cvt_pk_bf16_f32 v215, v94, v95
	v_cvt_pk_bf16_f32 v216, v64, v65
	v_cvt_pk_bf16_f32 v217, v66, v67
	v_cvt_pk_bf16_f32 v218, v68, v69
	v_cvt_pk_bf16_f32 v219, v70, v71
	v_cvt_pk_bf16_f32 v220, v72, v73
	v_cvt_pk_bf16_f32 v221, v74, v75
	v_cvt_pk_bf16_f32 v222, v76, v77
	v_cvt_pk_bf16_f32 v223, v78, v79
	s_nop 1
	s_waitcnt lgkmcnt(7)
	v_mfma_f32_32x32x16_bf16 v[80:95], v[196:199], v[140:143], 0
	ds_read_b128 v[244:247], v191 offset:33024
	s_waitcnt lgkmcnt(7)
	v_mfma_f32_32x32x16_bf16 v[80:95], v[200:203], v[136:139], v[80:95]
	ds_read_b128 v[248:251], v191 offset:33056
	v_add_u32_e32 v181, s100, v185
	s_waitcnt vmcnt(0)
	ds_write_b128 v181, v[144:147]
	s_waitcnt lgkmcnt(8)
	v_mfma_f32_32x32x16_bf16 v[80:95], v[204:207], v[132:135], v[80:95]
	ds_read_b128 v[196:199], v191 offset:33088
	v_add_u32_e32 v181, s100, v186
	ds_write_b128 v181, v[148:151]
	s_waitcnt lgkmcnt(9)
	v_mfma_f32_32x32x16_bf16 v[80:95], v[224:227], v[128:131], v[80:95]
	ds_read_b128 v[200:203], v191 offset:33120
	v_add_u32_e32 v181, s4, v172
	ds_write_b128 v181, v[152:155] offset:32768
	s_waitcnt lgkmcnt(10)
	v_mfma_f32_32x32x16_bf16 v[80:95], v[228:231], v[124:127], v[80:95]
	ds_read_b128 v[204:207], v191 offset:45568
	ds_write_b128 v181, v[156:159] offset:45568
	s_waitcnt lgkmcnt(11)
	v_mfma_f32_32x32x16_bf16 v[80:95], v[232:235], v[120:123], v[80:95]
	ds_read_b128 v[224:227], v191 offset:45600
	v_add_u32_e32 v181, s4, v188
	ds_write_b128 v181, v[160:163] offset:32768
	s_waitcnt lgkmcnt(12)
	v_mfma_f32_32x32x16_bf16 v[80:95], v[236:239], v[116:119], v[80:95]
	ds_read_b128 v[228:231], v191 offset:45632
	s_cmp_ge_u32 s1, s6
	s_cbranch_scc1 .Lfa_skipload
	global_load_dwordx4 v[144:147], v174, s[82:83]
	global_load_dwordx4 v[148:151], v175, s[82:83]
	global_load_dwordx4 v[152:155], v176, s[34:35]
	global_load_dwordx4 v[156:159], v177, s[34:35]
	global_load_dwordx4 v[160:163], v178, s[34:35] offset:256
	s_add_u32 s34, s34, 0x60000
	s_addc_u32 s35, s35, 0
	s_add_u32 s82, s82, 0x40000
	s_addc_u32 s83, s83, 0

; #define SCHEDB() __builtin_amdgcn_sched_barrier(0)
; template <bool FIX>
; DEVI void attn_item(const bfr* __restrict__ Qb, const bfr* __restrict__ Kh, const bfr* __restrict__ Vh, bfr* __restrict__ Ob, int seq, char* lds, float negBC) {
;     ...
;     finishSM(pA0, pA1, alA, l_reg, pa0, pa1, pa2, pa3); SCHEDB();
;     __builtin_amdgcn_s_setprio(1); pv_d0(o, vb0 + buf * SHM_V, pa0, pa1, pa2, pa3); __builtin_amdgcn_s_setprio(0);
;     __syncthreads();
;   }
.Lfa_end:
	s_mov_b32 s100, s101
	s_waitcnt lgkmcnt(0)
	s_cmp_eq_u32 s0, s1
	s_barrier
	s_cbranch_scc0 .LBB0_121
	s_branch .Lfa_drain
